# version 95 plus residual-GEMM loop: the 14 LDS-DMA prefetches of tiles beyond the end are not issued in the last K-iteration (exact waits vmcnt 2/0/0 on that path)
# speedup vs baseline: 1.0097x; 1.0006x over previous
; #define PG8_STAGE(bufoff, gbase, voff) do { _Pragma("unroll") for (int _i = 0; _i < 2; ++_i) \
;         __builtin_amdgcn_global_load_lds((const unsigned*)((const char*)(gbase) + (voff)[_i]), (PG8_LAS unsigned*)(lds + (bufoff) + ldsw + _i * 8192), 16, 0, 0); } while (0)
; #define PG8_LDA(dst, b, h) do { _Pragma("unroll") for (int m = 0; m < 4; ++m) _Pragma("unroll") for (int k = 0; k < 2; ++k) dst[m][k] = *(const PG8_LAS bf16x8*)(lds + PG8_SA(b, h) + aoff + m * 2048 + k * 1024); } while (0)
; #define PG8_LDB(dst, b, h) do { _Pragma("unroll") for (int n = 0; n < 2; ++n) _Pragma("unroll") for (int k = 0; k < 2; ++k) dst[n][k] = *(const PG8_LAS bf16x8*)(lds + PG8_SB(b, h) + boff + n * 2048 + k * 1024); } while (0)
; #define PG8_MMA(ai, bj, At, Bt) do { __builtin_amdgcn_s_setprio(1); _Pragma("unroll") for (int m = 0; m < 4; ++m) _Pragma("unroll") for (int n = 0; n < 2; ++n) _Pragma("unroll") for (int k = 0; k < 2; ++k) \
;         acc[ai][bj][m][n] = __builtin_amdgcn_mfma_f32_16x16x32_bf16(Bt[n][k], At[m][k], acc[ai][bj][m][n], 0, 0, 0); __builtin_amdgcn_s_setprio(0); } while (0)
; #define PG8_WAIT_V(n) asm volatile("s_waitcnt vmcnt(" #n ")" ::: "memory")
; #define PG8_WAIT_L(n) asm volatile("s_waitcnt lgkmcnt(" #n ")" ::: "memory")
; #define PG8_BAR __builtin_amdgcn_s_barrier()
; #define PG8_SCHED __builtin_amdgcn_sched_barrier(0)
; template <class Epi, class Sched, bool ALIGN_EPI = false, bool SP2 = false>
; __device__ __forceinline__ void gemm_phase(PG8_LAS unsigned char* lds, const Gemm g, const Sched& S, const Epi& E, const int tid_in) {
;     ...
;             const bool last = (t == nt - 2);
;             const char* a1 = cA + (size_t)(t + 1) * kstep;
;             const char* a2 = last ? nA : cA + (size_t)(t + 2) * kstep; const char* b2 = last ? nB : cB + (size_t)(t + 2) * kstep;
;             const char* a3 = a2 + kstep; const char* b3 = b2 + kstep;
;             if (last && has_next) S.a_ready(nxt);
;             if constexpr (SP2) {
;             PG8_LDB(B0, 0, 0); PG8_LDB(B1, 0, 1); PG8_SCHED; PG8_LDA(At, 0, 0); PG8_STAGE(PG8_SA(1, 1), a1 + hstep, voffA);
;             PG8_WAIT_V(8); PG8_WAIT_L(0); PG8_BAR; PG8_MMA(0, 0, At, B0); PG8_MMA(0, 1, At, B1); PG8_BAR; PG8_SCHED;
;             PG8_LDA(At, 0, 1); PG8_STAGE(PG8_SB(0, 0), b2, voffB); PG8_STAGE(PG8_SB(0, 1), b2 + hstep, voffB); PG8_STAGE(PG8_SA(0, 0), a2, voffA);
.LBB0_177:
	s_add_i32 s51, s12, 2
	s_add_u32 s52, s10, 0x80
	s_addc_u32 s13, s11, 0
	s_add_i32 s54, 0, 0x10000
	s_cmp_eq_u32 s31, s12
	s_cselect_b32 s13, s1, s13
	s_cselect_b32 s12, s0, s52
	s_cselect_b32 s53, s45, s15
	s_cselect_b32 s52, s44, s14
	s_cselect_b64 vcc, exec, 0
	s_add_i32 s55, 0, 0x14000
	v_add_u32_e32 v138, s54, v247
	v_add_u32_e32 v154, s55, v247
	ds_read_b128 v[126:129], v138
	ds_read_b128 v[130:133], v138 offset:1024
	ds_read_b128 v[134:137], v138 offset:2048
	ds_read_b128 v[138:141], v138 offset:3072
	ds_read_b128 v[142:145], v154
	ds_read_b128 v[146:149], v154 offset:1024
	ds_read_b128 v[150:153], v154 offset:2048
	ds_read_b128 v[154:157], v154 offset:3072
	v_lshl_add_u64 v[214:215], s[10:11], 0, v[206:207]
	s_add_i32 m0, s18, 0xc000
	ds_read_b128 v[158:161], v249
	ds_read_b128 v[162:165], v249 offset:1024
	ds_read_b128 v[170:173], v249 offset:2048
	ds_read_b128 v[178:181], v249 offset:3072
	ds_read_b128 v[182:185], v249 offset:4096
	ds_read_b128 v[186:189], v249 offset:5120
	ds_read_b128 v[190:193], v249 offset:6144
	ds_read_b128 v[210:213], v249 offset:7168
	global_load_lds_dwordx4 v[214:215], off
	v_lshl_add_u64 v[214:215], s[10:11], 0, v[208:209]
	s_add_i32 m0, s18, 0xe000
	s_nop 0
	global_load_lds_dwordx4 v[214:215], off
	s_nop 0
	s_waitcnt vmcnt(8)
	s_waitcnt lgkmcnt(0)
	s_barrier
	v_mfma_f32_16x16x32_bf16 v[174:177], v[126:129], v[158:161], v[174:177]
	v_mfma_f32_16x16x32_bf16 v[174:177], v[130:133], v[162:165], v[174:177]
	v_mfma_f32_16x16x32_bf16 v[114:117], v[126:129], v[170:173], v[114:117]
	v_mfma_f32_16x16x32_bf16 v[114:117], v[130:133], v[178:181], v[114:117]
	v_mfma_f32_16x16x32_bf16 v[98:101], v[126:129], v[182:185], v[98:101]
	v_mfma_f32_16x16x32_bf16 v[98:101], v[130:133], v[186:189], v[98:101]
	v_mfma_f32_16x16x32_bf16 v[82:85], v[126:129], v[190:193], v[82:85]
	v_mfma_f32_16x16x32_bf16 v[82:85], v[130:133], v[210:213], v[82:85]
	v_mfma_f32_16x16x32_bf16 v[166:169], v[134:137], v[158:161], v[166:169]
	v_mfma_f32_16x16x32_bf16 v[166:169], v[138:141], v[162:165], v[166:169]
	v_mfma_f32_16x16x32_bf16 v[110:113], v[134:137], v[170:173], v[110:113]
	v_mfma_f32_16x16x32_bf16 v[110:113], v[138:141], v[178:181], v[110:113]
	v_mfma_f32_16x16x32_bf16 v[94:97], v[134:137], v[182:185], v[94:97]
	v_mfma_f32_16x16x32_bf16 v[94:97], v[138:141], v[186:189], v[94:97]
	v_mfma_f32_16x16x32_bf16 v[78:81], v[134:137], v[190:193], v[78:81]
	v_mfma_f32_16x16x32_bf16 v[78:81], v[138:141], v[210:213], v[78:81]
	v_mfma_f32_16x16x32_bf16 v[122:125], v[142:145], v[158:161], v[122:125]
	v_mfma_f32_16x16x32_bf16 v[122:125], v[146:149], v[162:165], v[122:125]
	v_mfma_f32_16x16x32_bf16 v[106:109], v[142:145], v[170:173], v[106:109]
	v_mfma_f32_16x16x32_bf16 v[106:109], v[146:149], v[178:181], v[106:109]
	v_mfma_f32_16x16x32_bf16 v[90:93], v[142:145], v[182:185], v[90:93]
	v_mfma_f32_16x16x32_bf16 v[90:93], v[146:149], v[186:189], v[90:93]
	v_mfma_f32_16x16x32_bf16 v[74:77], v[142:145], v[190:193], v[74:77]
	v_mfma_f32_16x16x32_bf16 v[74:77], v[146:149], v[210:213], v[74:77]
	v_mfma_f32_16x16x32_bf16 v[118:121], v[150:153], v[158:161], v[118:121]
	v_mfma_f32_16x16x32_bf16 v[118:121], v[154:157], v[162:165], v[118:121]
	v_mfma_f32_16x16x32_bf16 v[102:105], v[150:153], v[170:173], v[102:105]
	v_mfma_f32_16x16x32_bf16 v[102:105], v[154:157], v[178:181], v[102:105]
	v_mfma_f32_16x16x32_bf16 v[86:89], v[150:153], v[182:185], v[86:89]
	v_mfma_f32_16x16x32_bf16 v[86:89], v[154:157], v[186:189], v[86:89]
	v_mfma_f32_16x16x32_bf16 v[70:73], v[150:153], v[190:193], v[70:73]
	v_mfma_f32_16x16x32_bf16 v[70:73], v[154:157], v[210:213], v[70:73]
	s_barrier
	s_add_i32 s54, s54, s17
	v_lshl_add_u64 v[214:215], s[52:53], 0, v[202:203]
	s_mov_b32 m0, s54
	ds_read_b128 v[158:161], v249 offset:16384
	ds_read_b128 v[162:165], v249 offset:17408
	ds_read_b128 v[170:173], v249 offset:18432
	ds_read_b128 v[178:181], v249 offset:19456
	ds_read_b128 v[182:185], v249 offset:20480
	ds_read_b128 v[186:189], v249 offset:21504
	ds_read_b128 v[190:193], v249 offset:22528
	ds_read_b128 v[210:213], v249 offset:23552
	s_cbranch_vccnz .Lrt_skip_1
	global_load_lds_dwordx4 v[214:215], off
	s_add_i32 m0, s54, 0x2000
	v_lshl_add_u64 v[216:217], s[52:53], 0, v[198:199]
	s_add_u32 s52, s52, s62
	s_addc_u32 s53, s53, 0
	s_add_i32 s54, s55, s17
	global_load_lds_dwordx4 v[216:217], off
	v_lshl_add_u64 v[218:219], s[52:53], 0, v[202:203]
	s_mov_b32 m0, s54
	v_lshl_add_u64 v[220:221], s[52:53], 0, v[198:199]
	global_load_lds_dwordx4 v[218:219], off
	s_add_i32 m0, s54, 0x2000
	v_lshl_add_u64 v[222:223], s[12:13], 0, v[204:205]
	global_load_lds_dwordx4 v[220:221], off
	s_mov_b32 m0, s18
	v_lshl_add_u64 v[224:225], s[12:13], 0, v[200:201]
	global_load_lds_dwordx4 v[222:223], off
	s_mov_b32 m0, s19
	s_nop 0
	global_load_lds_dwordx4 v[224:225], off
	s_nop 0
	s_nop 0
	s_waitcnt vmcnt(8)
	s_branch .Lrt_join_1

; #define PG8_STAGE(bufoff, gbase, voff) do { _Pragma("unroll") for (int _i = 0; _i < 2; ++_i) \
;         __builtin_amdgcn_global_load_lds((const unsigned*)((const char*)(gbase) + (voff)[_i]), (PG8_LAS unsigned*)(lds + (bufoff) + ldsw + _i * 8192), 16, 0, 0); } while (0)
; #define PG8_LDA(dst, b, h) do { _Pragma("unroll") for (int m = 0; m < 4; ++m) _Pragma("unroll") for (int k = 0; k < 2; ++k) dst[m][k] = *(const PG8_LAS bf16x8*)(lds + PG8_SA(b, h) + aoff + m * 2048 + k * 1024); } while (0)
; #define PG8_LDB(dst, b, h) do { _Pragma("unroll") for (int n = 0; n < 2; ++n) _Pragma("unroll") for (int k = 0; k < 2; ++k) dst[n][k] = *(const PG8_LAS bf16x8*)(lds + PG8_SB(b, h) + boff + n * 2048 + k * 1024); } while (0)
; #define PG8_MMA(ai, bj, At, Bt) do { __builtin_amdgcn_s_setprio(1); _Pragma("unroll") for (int m = 0; m < 4; ++m) _Pragma("unroll") for (int n = 0; n < 2; ++n) _Pragma("unroll") for (int k = 0; k < 2; ++k) \
;         acc[ai][bj][m][n] = __builtin_amdgcn_mfma_f32_16x16x32_bf16(Bt[n][k], At[m][k], acc[ai][bj][m][n], 0, 0, 0); __builtin_amdgcn_s_setprio(0); } while (0)
; #define PG8_WAIT_V(n) asm volatile("s_waitcnt vmcnt(" #n ")" ::: "memory")
; #define PG8_WAIT_L(n) asm volatile("s_waitcnt lgkmcnt(" #n ")" ::: "memory")
; #define PG8_BAR __builtin_amdgcn_s_barrier()
; #define PG8_SCHED __builtin_amdgcn_sched_barrier(0)
; template <class Epi, class Sched, bool ALIGN_EPI = false, bool SP2 = false>
; __device__ __forceinline__ void gemm_phase(PG8_LAS unsigned char* lds, const Gemm g, const Sched& S, const Epi& E, const int tid_in) {
;     ...
;             PG8_LDA(At, 0, 1); PG8_STAGE(PG8_SB(0, 0), b2, voffB); PG8_STAGE(PG8_SB(0, 1), b2 + hstep, voffB); PG8_STAGE(PG8_SA(0, 0), a2, voffA);
;             PG8_WAIT_V(8); PG8_WAIT_L(0); PG8_BAR; PG8_MMA(1, 0, At, B0); PG8_MMA(1, 1, At, B1); PG8_BAR; PG8_SCHED;
;             PG8_LDB(B0, 1, 0); PG8_LDB(B1, 1, 1); PG8_SCHED; PG8_LDA(At, 1, 0); PG8_STAGE(PG8_SA(0, 1), a2 + hstep, voffA);
;             PG8_WAIT_V(8); PG8_WAIT_L(0); PG8_BAR; PG8_MMA(0, 0, At, B0); PG8_MMA(0, 1, At, B1); PG8_BAR; PG8_SCHED;
.Lrt_join_1:
	s_waitcnt lgkmcnt(0)
	s_barrier
	v_mfma_f32_16x16x32_bf16 v[66:69], v[126:129], v[158:161], v[66:69]
	v_mfma_f32_16x16x32_bf16 v[66:69], v[130:133], v[162:165], v[66:69]
	v_mfma_f32_16x16x32_bf16 v[50:53], v[126:129], v[170:173], v[50:53]
	v_mfma_f32_16x16x32_bf16 v[50:53], v[130:133], v[178:181], v[50:53]
	v_mfma_f32_16x16x32_bf16 v[34:37], v[126:129], v[182:185], v[34:37]
	v_mfma_f32_16x16x32_bf16 v[34:37], v[130:133], v[186:189], v[34:37]
	v_mfma_f32_16x16x32_bf16 v[18:21], v[126:129], v[190:193], v[18:21]
	v_mfma_f32_16x16x32_bf16 v[18:21], v[130:133], v[210:213], v[18:21]
	v_mfma_f32_16x16x32_bf16 v[62:65], v[134:137], v[158:161], v[62:65]
	v_mfma_f32_16x16x32_bf16 v[62:65], v[138:141], v[162:165], v[62:65]
	v_mfma_f32_16x16x32_bf16 v[46:49], v[134:137], v[170:173], v[46:49]
	v_mfma_f32_16x16x32_bf16 v[46:49], v[138:141], v[178:181], v[46:49]
	v_mfma_f32_16x16x32_bf16 v[30:33], v[134:137], v[182:185], v[30:33]
	v_mfma_f32_16x16x32_bf16 v[30:33], v[138:141], v[186:189], v[30:33]
	v_mfma_f32_16x16x32_bf16 v[14:17], v[134:137], v[190:193], v[14:17]
	v_mfma_f32_16x16x32_bf16 v[14:17], v[138:141], v[210:213], v[14:17]
	v_mfma_f32_16x16x32_bf16 v[58:61], v[142:145], v[158:161], v[58:61]
	v_mfma_f32_16x16x32_bf16 v[58:61], v[146:149], v[162:165], v[58:61]
	v_mfma_f32_16x16x32_bf16 v[42:45], v[142:145], v[170:173], v[42:45]
	v_mfma_f32_16x16x32_bf16 v[42:45], v[146:149], v[178:181], v[42:45]
	v_mfma_f32_16x16x32_bf16 v[26:29], v[142:145], v[182:185], v[26:29]
	v_mfma_f32_16x16x32_bf16 v[26:29], v[146:149], v[186:189], v[26:29]
	v_mfma_f32_16x16x32_bf16 v[10:13], v[142:145], v[190:193], v[10:13]
	v_mfma_f32_16x16x32_bf16 v[10:13], v[146:149], v[210:213], v[10:13]
	v_mfma_f32_16x16x32_bf16 v[54:57], v[150:153], v[158:161], v[54:57]
	v_mfma_f32_16x16x32_bf16 v[54:57], v[154:157], v[162:165], v[54:57]
	v_mfma_f32_16x16x32_bf16 v[38:41], v[150:153], v[170:173], v[38:41]
	v_mfma_f32_16x16x32_bf16 v[38:41], v[154:157], v[178:181], v[38:41]
	v_mfma_f32_16x16x32_bf16 v[22:25], v[150:153], v[182:185], v[22:25]
	v_mfma_f32_16x16x32_bf16 v[22:25], v[154:157], v[186:189], v[22:25]
	v_mfma_f32_16x16x32_bf16 v[6:9], v[150:153], v[190:193], v[6:9]
	v_mfma_f32_16x16x32_bf16 v[6:9], v[154:157], v[210:213], v[6:9]
	s_barrier
	s_add_i32 s52, 0, 0x18000
	s_add_i32 s53, 0, 0x1c000
	v_add_u32_e32 v138, s52, v247
	v_add_u32_e32 v154, s53, v247
	ds_read_b128 v[126:129], v138
	ds_read_b128 v[130:133], v138 offset:1024
	ds_read_b128 v[134:137], v138 offset:2048
	ds_read_b128 v[138:141], v138 offset:3072
	ds_read_b128 v[142:145], v154
	ds_read_b128 v[146:149], v154 offset:1024
	ds_read_b128 v[150:153], v154 offset:2048
	ds_read_b128 v[154:157], v154 offset:3072
	s_add_u32 s12, s12, s62
	s_addc_u32 s13, s13, 0
	s_mov_b32 m0, s22
	v_lshl_add_u64 v[226:227], s[12:13], 0, v[204:205]
	ds_read_b128 v[158:161], v249 offset:32768
	ds_read_b128 v[162:165], v249 offset:33792
	ds_read_b128 v[170:173], v249 offset:34816
	ds_read_b128 v[178:181], v249 offset:35840
	ds_read_b128 v[182:185], v249 offset:36864
	ds_read_b128 v[186:189], v249 offset:37888
	ds_read_b128 v[190:193], v249 offset:38912
	ds_read_b128 v[210:213], v249 offset:39936
	s_cbranch_vccnz .Lrt_skip_2
	global_load_lds_dwordx4 v[226:227], off
	v_lshl_add_u64 v[226:227], s[12:13], 0, v[200:201]
	s_mov_b32 m0, s23
	s_nop 0
	global_load_lds_dwordx4 v[226:227], off
	s_nop 0
	s_nop 0
	s_waitcnt vmcnt(8)
	s_branch .Lrt_join_2

; #define PG8_STAGE(bufoff, gbase, voff) do { _Pragma("unroll") for (int _i = 0; _i < 2; ++_i) \
;         __builtin_amdgcn_global_load_lds((const unsigned*)((const char*)(gbase) + (voff)[_i]), (PG8_LAS unsigned*)(lds + (bufoff) + ldsw + _i * 8192), 16, 0, 0); } while (0)
; #define PG8_LDA(dst, b, h) do { _Pragma("unroll") for (int m = 0; m < 4; ++m) _Pragma("unroll") for (int k = 0; k < 2; ++k) dst[m][k] = *(const PG8_LAS bf16x8*)(lds + PG8_SA(b, h) + aoff + m * 2048 + k * 1024); } while (0)
; #define PG8_MMA(ai, bj, At, Bt) do { __builtin_amdgcn_s_setprio(1); _Pragma("unroll") for (int m = 0; m < 4; ++m) _Pragma("unroll") for (int n = 0; n < 2; ++n) _Pragma("unroll") for (int k = 0; k < 2; ++k) \
;         acc[ai][bj][m][n] = __builtin_amdgcn_mfma_f32_16x16x32_bf16(Bt[n][k], At[m][k], acc[ai][bj][m][n], 0, 0, 0); __builtin_amdgcn_s_setprio(0); } while (0)
; #define PG8_WAIT_V(n) asm volatile("s_waitcnt vmcnt(" #n ")" ::: "memory")
; #define PG8_WAIT_L(n) asm volatile("s_waitcnt lgkmcnt(" #n ")" ::: "memory")
; #define PG8_BAR __builtin_amdgcn_s_barrier()
; #define PG8_SCHED __builtin_amdgcn_sched_barrier(0)
; template <class Epi, class Sched, bool ALIGN_EPI = false, bool SP2 = false>
; __device__ __forceinline__ void gemm_phase(PG8_LAS unsigned char* lds, const Gemm g, const Sched& S, const Epi& E, const int tid_in) {
;     ...
;             PG8_WAIT_V(8); PG8_WAIT_L(0); PG8_BAR; PG8_MMA(0, 0, At, B0); PG8_MMA(0, 1, At, B1); PG8_BAR; PG8_SCHED;
;             PG8_LDA(At, 1, 1); PG8_STAGE(PG8_SB(1, 0), b3, voffB); PG8_STAGE(PG8_SB(1, 1), b3 + hstep, voffB); PG8_STAGE(PG8_SA(1, 0), a3, voffA);
;             PG8_WAIT_V(8); PG8_WAIT_L(0); PG8_BAR; PG8_MMA(1, 0, At, B0); PG8_MMA(1, 1, At, B1); PG8_BAR; PG8_SCHED;
.Lrt_join_2:
	s_waitcnt lgkmcnt(0)
	s_barrier
	v_mfma_f32_16x16x32_bf16 v[174:177], v[126:129], v[158:161], v[174:177]
	v_mfma_f32_16x16x32_bf16 v[174:177], v[130:133], v[162:165], v[174:177]
	v_mfma_f32_16x16x32_bf16 v[114:117], v[126:129], v[170:173], v[114:117]
	v_mfma_f32_16x16x32_bf16 v[114:117], v[130:133], v[178:181], v[114:117]
	v_mfma_f32_16x16x32_bf16 v[98:101], v[126:129], v[182:185], v[98:101]
	v_mfma_f32_16x16x32_bf16 v[98:101], v[130:133], v[186:189], v[98:101]
	v_mfma_f32_16x16x32_bf16 v[82:85], v[126:129], v[190:193], v[82:85]
	v_mfma_f32_16x16x32_bf16 v[82:85], v[130:133], v[210:213], v[82:85]
	v_mfma_f32_16x16x32_bf16 v[166:169], v[134:137], v[158:161], v[166:169]
	v_mfma_f32_16x16x32_bf16 v[166:169], v[138:141], v[162:165], v[166:169]
	v_mfma_f32_16x16x32_bf16 v[110:113], v[134:137], v[170:173], v[110:113]
	v_mfma_f32_16x16x32_bf16 v[110:113], v[138:141], v[178:181], v[110:113]
	v_mfma_f32_16x16x32_bf16 v[94:97], v[134:137], v[182:185], v[94:97]
	v_mfma_f32_16x16x32_bf16 v[94:97], v[138:141], v[186:189], v[94:97]
	v_mfma_f32_16x16x32_bf16 v[78:81], v[134:137], v[190:193], v[78:81]
	v_mfma_f32_16x16x32_bf16 v[78:81], v[138:141], v[210:213], v[78:81]
	v_mfma_f32_16x16x32_bf16 v[122:125], v[142:145], v[158:161], v[122:125]
	v_mfma_f32_16x16x32_bf16 v[122:125], v[146:149], v[162:165], v[122:125]
	v_mfma_f32_16x16x32_bf16 v[106:109], v[142:145], v[170:173], v[106:109]
	v_mfma_f32_16x16x32_bf16 v[106:109], v[146:149], v[178:181], v[106:109]
	v_mfma_f32_16x16x32_bf16 v[90:93], v[142:145], v[182:185], v[90:93]
	v_mfma_f32_16x16x32_bf16 v[90:93], v[146:149], v[186:189], v[90:93]
	v_mfma_f32_16x16x32_bf16 v[74:77], v[142:145], v[190:193], v[74:77]
	v_mfma_f32_16x16x32_bf16 v[74:77], v[146:149], v[210:213], v[74:77]
	v_mfma_f32_16x16x32_bf16 v[118:121], v[150:153], v[158:161], v[118:121]
	v_mfma_f32_16x16x32_bf16 v[118:121], v[154:157], v[162:165], v[118:121]
	v_mfma_f32_16x16x32_bf16 v[102:105], v[150:153], v[170:173], v[102:105]
	v_mfma_f32_16x16x32_bf16 v[102:105], v[154:157], v[178:181], v[102:105]
	v_mfma_f32_16x16x32_bf16 v[86:89], v[150:153], v[182:185], v[86:89]
	v_mfma_f32_16x16x32_bf16 v[86:89], v[154:157], v[186:189], v[86:89]
	v_mfma_f32_16x16x32_bf16 v[70:73], v[150:153], v[190:193], v[70:73]
	v_mfma_f32_16x16x32_bf16 v[70:73], v[154:157], v[210:213], v[70:73]
	s_barrier
	s_add_i32 s12, s52, s17
	v_lshl_add_u64 v[214:215], v[214:215], 0, s[28:29]
	s_mov_b32 m0, s12
	ds_read_b128 v[158:161], v249 offset:49152
	ds_read_b128 v[162:165], v249 offset:50176
	ds_read_b128 v[170:173], v249 offset:51200
	ds_read_b128 v[178:181], v249 offset:52224
	ds_read_b128 v[182:185], v249 offset:53248
	ds_read_b128 v[186:189], v249 offset:54272
	ds_read_b128 v[190:193], v249 offset:55296
	ds_read_b128 v[210:213], v249 offset:56320
	s_cbranch_vccnz .Lrt_skip_3
	global_load_lds_dwordx4 v[214:215], off
	v_lshl_add_u64 v[214:215], v[216:217], 0, s[28:29]
	s_add_i32 m0, s12, 0x2000
	s_add_i32 s12, s53, s17
	global_load_lds_dwordx4 v[214:215], off
	v_lshl_add_u64 v[214:215], v[218:219], 0, s[28:29]
	s_mov_b32 m0, s12
	s_nop 0
	global_load_lds_dwordx4 v[214:215], off
	v_lshl_add_u64 v[214:215], v[220:221], 0, s[28:29]
	s_add_i32 m0, s12, 0x2000
	s_nop 0
	global_load_lds_dwordx4 v[214:215], off
	v_lshl_add_u64 v[214:215], v[222:223], 0, s[28:29]
	s_mov_b32 m0, s26
	s_nop 0
	global_load_lds_dwordx4 v[214:215], off
	v_lshl_add_u64 v[214:215], v[224:225], 0, s[28:29]
	s_mov_b32 m0, s27
	s_nop 0
	global_load_lds_dwordx4 v[214:215], off
	s_nop 0
	s_waitcnt vmcnt(8)
	s_branch .Lrt_join_3

; #define PG8_STAGE(bufoff, gbase, voff) do { _Pragma("unroll") for (int _i = 0; _i < 2; ++_i) \
;         __builtin_amdgcn_global_load_lds((const unsigned*)((const char*)(gbase) + (voff)[_i]), (PG8_LAS unsigned*)(lds + (bufoff) + ldsw + _i * 8192), 16, 0, 0); } while (0)
; #define PG8_LDA(dst, b, h) do { _Pragma("unroll") for (int m = 0; m < 4; ++m) _Pragma("unroll") for (int k = 0; k < 2; ++k) dst[m][k] = *(const PG8_LAS bf16x8*)(lds + PG8_SA(b, h) + aoff + m * 2048 + k * 1024); } while (0)
; #define PG8_MMA(ai, bj, At, Bt) do { __builtin_amdgcn_s_setprio(1); _Pragma("unroll") for (int m = 0; m < 4; ++m) _Pragma("unroll") for (int n = 0; n < 2; ++n) _Pragma("unroll") for (int k = 0; k < 2; ++k) \
;         acc[ai][bj][m][n] = __builtin_amdgcn_mfma_f32_16x16x32_bf16(Bt[n][k], At[m][k], acc[ai][bj][m][n], 0, 0, 0); __builtin_amdgcn_s_setprio(0); } while (0)
; #define PG8_WAIT_V(n) asm volatile("s_waitcnt vmcnt(" #n ")" ::: "memory")
; #define PG8_WAIT_L(n) asm volatile("s_waitcnt lgkmcnt(" #n ")" ::: "memory")
; #define PG8_BAR __builtin_amdgcn_s_barrier()
; #define PG8_SCHED __builtin_amdgcn_sched_barrier(0)
; template <class Epi, class Sched, bool ALIGN_EPI = false, bool SP2 = false>
; __device__ __forceinline__ void gemm_phase(PG8_LAS unsigned char* lds, const Gemm g, const Sched& S, const Epi& E, const int tid_in) {
;     ...
;         for (int t = 0; t < nt; t += 2) {
;             const bool last = (t == nt - 2);
;     ...
;             PG8_WAIT_V(8); PG8_WAIT_L(0); PG8_BAR; PG8_MMA(0, 0, At, B0); PG8_MMA(0, 1, At, B1); PG8_BAR; PG8_SCHED;
;             PG8_LDA(At, 1, 1); PG8_STAGE(PG8_SB(1, 0), b3, voffB); PG8_STAGE(PG8_SB(1, 1), b3 + hstep, voffB); PG8_STAGE(PG8_SA(1, 0), a3, voffA);
;             PG8_WAIT_V(8); PG8_WAIT_L(0); PG8_BAR; PG8_MMA(1, 0, At, B0); PG8_MMA(1, 1, At, B1); PG8_BAR; PG8_SCHED;
.Lrt_join_3:
	s_waitcnt lgkmcnt(0)
	s_barrier
	v_mfma_f32_16x16x32_bf16 v[66:69], v[126:129], v[158:161], v[66:69]
	v_mfma_f32_16x16x32_bf16 v[66:69], v[130:133], v[162:165], v[66:69]
	v_mfma_f32_16x16x32_bf16 v[50:53], v[126:129], v[170:173], v[50:53]
	v_mfma_f32_16x16x32_bf16 v[50:53], v[130:133], v[178:181], v[50:53]
	v_mfma_f32_16x16x32_bf16 v[34:37], v[126:129], v[182:185], v[34:37]
	v_mfma_f32_16x16x32_bf16 v[34:37], v[130:133], v[186:189], v[34:37]
	v_mfma_f32_16x16x32_bf16 v[18:21], v[126:129], v[190:193], v[18:21]
	v_mfma_f32_16x16x32_bf16 v[18:21], v[130:133], v[210:213], v[18:21]
	v_mfma_f32_16x16x32_bf16 v[62:65], v[134:137], v[158:161], v[62:65]
	v_mfma_f32_16x16x32_bf16 v[62:65], v[138:141], v[162:165], v[62:65]
	v_mfma_f32_16x16x32_bf16 v[46:49], v[134:137], v[170:173], v[46:49]
	v_mfma_f32_16x16x32_bf16 v[46:49], v[138:141], v[178:181], v[46:49]
	v_mfma_f32_16x16x32_bf16 v[30:33], v[134:137], v[182:185], v[30:33]
	v_mfma_f32_16x16x32_bf16 v[30:33], v[138:141], v[186:189], v[30:33]
	v_mfma_f32_16x16x32_bf16 v[14:17], v[134:137], v[190:193], v[14:17]
	v_mfma_f32_16x16x32_bf16 v[14:17], v[138:141], v[210:213], v[14:17]
	v_mfma_f32_16x16x32_bf16 v[58:61], v[142:145], v[158:161], v[58:61]
	v_mfma_f32_16x16x32_bf16 v[58:61], v[146:149], v[162:165], v[58:61]
	v_mfma_f32_16x16x32_bf16 v[42:45], v[142:145], v[170:173], v[42:45]
	v_mfma_f32_16x16x32_bf16 v[42:45], v[146:149], v[178:181], v[42:45]
	v_mfma_f32_16x16x32_bf16 v[26:29], v[142:145], v[182:185], v[26:29]
	v_mfma_f32_16x16x32_bf16 v[26:29], v[146:149], v[186:189], v[26:29]
	v_mfma_f32_16x16x32_bf16 v[10:13], v[142:145], v[190:193], v[10:13]
	v_mfma_f32_16x16x32_bf16 v[10:13], v[146:149], v[210:213], v[10:13]
	v_mfma_f32_16x16x32_bf16 v[54:57], v[150:153], v[158:161], v[54:57]
	v_mfma_f32_16x16x32_bf16 v[54:57], v[154:157], v[162:165], v[54:57]
	v_mfma_f32_16x16x32_bf16 v[38:41], v[150:153], v[170:173], v[38:41]
	v_mfma_f32_16x16x32_bf16 v[38:41], v[154:157], v[178:181], v[38:41]
	v_mfma_f32_16x16x32_bf16 v[22:25], v[150:153], v[182:185], v[22:25]
	v_mfma_f32_16x16x32_bf16 v[22:25], v[154:157], v[186:189], v[22:25]
	v_mfma_f32_16x16x32_bf16 v[6:9], v[150:153], v[190:193], v[6:9]
	v_mfma_f32_16x16x32_bf16 v[6:9], v[154:157], v[210:213], v[6:9]
	s_barrier
	s_add_u32 s10, s10, 0x100
	s_addc_u32 s11, s11, 0
	s_add_u32 s14, s14, 0x100
	s_addc_u32 s15, s15, 0
	s_cmp_ge_u32 s51, s30
	s_mov_b32 s12, s51
	s_cbranch_scc0 .LBB0_177
	s_and_b64 vcc, exec, s[42:43]
	s_cbranch_vccz .LBB0_180
	s_barrier
